# v23 + P0 weight-prep loads batched (W_in, W_ukv) + GLA decay-stage LDS reads hoisted
# speedup vs baseline: 1.0200x; 1.0081x over previous
; __device__ __forceinline__ void prep_item(const Params& p, int l, int mat, int n, int kc, unsigned char* wl) {
;     ...
;         const float* src = p.w_in + (size_t)l * D * DIN;
; #pragma unroll
;         for (int i = 0; i < 8; ++i) v[i] = (col >= 0) ? sg * src[(size_t)(k0 + i) * DIN + col] : 0.f;
.LBB0_64:
	s_andn2_saveexec_b64 s[64:65], s[64:65]
	v_mov_b32_e32 v4, 1.0
	s_or_b64 exec, exec, s[64:65]
	v_lshlrev_b32_e32 v16, 3, v12
	v_mov_b32_e32 v15, v5
	v_ashrrev_i32_e32 v17, 31, v16
	v_cmp_lt_i32_e32 vcc, -1, v14
	v_lshl_add_u64 v[14:15], v[14:15], 2, s[58:59]
	v_mov_b32_e32 v18, 0
	v_mov_b32_e32 v19, 0
	v_mov_b32_e32 v23, 0
	v_mov_b32_e32 v22, 0
	v_mov_b32_e32 v25, 0
	v_mov_b32_e32 v24, 0
	v_mov_b32_e32 v27, 0
	v_mov_b32_e32 v26, 0
	s_and_saveexec_b64 s[64:65], vcc
	s_cbranch_execz .LBB0_17
	v_mad_i64_i32 v[28:29], s[66:67], v16, s37, v[14:15]
	global_load_dword v18, v[28:29], off
	v_or_b32_e32 v19, 1, v16
	v_mad_i64_i32 v[28:29], s[66:67], v19, s37, v[14:15]
	global_load_dword v19, v[28:29], off
	v_or_b32_e32 v23, 2, v16
	v_mad_i64_i32 v[28:29], s[66:67], v23, s37, v[14:15]
	global_load_dword v23, v[28:29], off
	v_or_b32_e32 v22, 3, v16
	v_mad_i64_i32 v[28:29], s[66:67], v22, s37, v[14:15]
	global_load_dword v22, v[28:29], off
	v_or_b32_e32 v25, 4, v16
	v_mad_i64_i32 v[28:29], s[66:67], v25, s37, v[14:15]
	global_load_dword v25, v[28:29], off
	v_or_b32_e32 v24, 5, v16
	v_mad_i64_i32 v[28:29], s[66:67], v24, s37, v[14:15]
	global_load_dword v24, v[28:29], off
	v_or_b32_e32 v27, 6, v16
	v_mad_i64_i32 v[28:29], s[66:67], v27, s37, v[14:15]
	global_load_dword v27, v[28:29], off
	v_or_b32_e32 v26, 7, v16
	v_mad_i64_i32 v[28:29], s[66:67], v26, s37, v[14:15]
	global_load_dword v26, v[28:29], off
	s_waitcnt vmcnt(0)
	v_mul_f32_e32 v18, v4, v18
	v_mul_f32_e32 v19, v4, v19
	v_mul_f32_e32 v23, v4, v23
	v_mul_f32_e32 v22, v4, v22
	v_mul_f32_e32 v25, v4, v25
	v_mul_f32_e32 v24, v4, v24
	v_mul_f32_e32 v27, v4, v27
	v_mul_f32_e32 v26, v4, v26
	s_branch .LBB0_17

; __device__ __forceinline__ void prep_item(const Params& p, int l, int mat, int n, int kc, unsigned char* wl) {
;     ...
;         dst = (bf16_t*)(wl + W_UKV) + (size_t)n * 256 + k0;
;         const int col = (n < 512) ? ((n >> 6) * 128 + (n & 63)) : (((n - 512) >> 6) * 128 + 64 + (n & 63));
;         const float* src = p.mla_w_ukv + (size_t)l * 128 * 1024 + col; const float* gn = p.mla_kv_norm + l * 128;
; #pragma unroll
;         for (int i = 0; i < 8; ++i) v[i] = (k0 < 128) ? gn[k0 + i] * src[(size_t)(k0 + i) * 1024] : 0.f;
.LBB0_102:
	v_ashrrev_i32_e32 v4, 31, v11
	v_lshrrev_b32_e32 v4, 22, v4
	v_lshl_add_u64 v[14:15], v[10:11], 0, v[4:5]
	v_ashrrev_i64 v[12:13], 10, v[14:15]
	v_and_b32_e32 v4, 0xfffffc00, v14
	v_sub_co_u32_e32 v16, vcc, v10, v4
	v_lshlrev_b32_e32 v4, 11, v12
	v_sub_u32_e32 v4, v22, v4
	v_subb_co_u32_e32 v17, vcc, v11, v15, vcc
	v_and_b32_e32 v18, 0x7fffff80, v4
	s_mov_b64 s[66:67], 0x200
	v_add_u32_e32 v18, 0xfffffc40, v18
	v_and_b32_e32 v4, 0xffffff80, v4
	v_cmp_gt_i64_e32 vcc, s[66:67], v[16:17]
	v_lshlrev_b32_e32 v14, 3, v12
	v_ashrrev_i32_e32 v15, 31, v14
	v_cndmask_b32_e32 v4, v18, v4, vcc
	v_and_or_b32 v16, v10, 63, v4
	v_ashrrev_i32_e32 v17, 31, v16
	v_lshl_add_u64 v[16:17], v[16:17], 2, s[60:61]
	v_cmp_gt_i32_e32 vcc, 16, v12
	v_lshl_add_u64 v[18:19], v[14:15], 2, s[62:63]
	v_mov_b32_e32 v4, 0
	v_mov_b32_e32 v23, 0
	v_mov_b32_e32 v25, 0
	v_mov_b32_e32 v24, 0
	v_mov_b32_e32 v27, 0
	v_mov_b32_e32 v26, 0
	v_mov_b32_e32 v29, 0
	v_mov_b32_e32 v28, 0
	s_and_saveexec_b64 s[66:67], vcc
	s_cbranch_execz .LBB0_101
	v_lshlrev_b64 v[38:39], 12, v[14:15]
	v_lshl_add_u64 v[38:39], v[16:17], 0, v[38:39]
	global_load_dword v30, v[18:19], off
	global_load_dword v4, v[38:39], off
	v_or_b32_e32 v38, 1, v14
	v_ashrrev_i32_e32 v39, 31, v38
	v_lshlrev_b64 v[38:39], 12, v[38:39]
	v_lshl_add_u64 v[38:39], v[16:17], 0, v[38:39]
	global_load_dword v31, v[18:19], off offset:4
	global_load_dword v23, v[38:39], off
	v_or_b32_e32 v38, 2, v14
	v_ashrrev_i32_e32 v39, 31, v38
	v_lshlrev_b64 v[38:39], 12, v[38:39]
	v_lshl_add_u64 v[38:39], v[16:17], 0, v[38:39]
	global_load_dword v32, v[18:19], off offset:8
	global_load_dword v25, v[38:39], off
	v_or_b32_e32 v38, 3, v14
	v_ashrrev_i32_e32 v39, 31, v38
	v_lshlrev_b64 v[38:39], 12, v[38:39]
	v_lshl_add_u64 v[38:39], v[16:17], 0, v[38:39]
	global_load_dword v33, v[18:19], off offset:12
	global_load_dword v24, v[38:39], off
	v_or_b32_e32 v38, 4, v14
	v_ashrrev_i32_e32 v39, 31, v38
	v_lshlrev_b64 v[38:39], 12, v[38:39]
	v_lshl_add_u64 v[38:39], v[16:17], 0, v[38:39]
	global_load_dword v34, v[18:19], off offset:16
	global_load_dword v27, v[38:39], off
	v_or_b32_e32 v38, 5, v14
	v_ashrrev_i32_e32 v39, 31, v38
	v_lshlrev_b64 v[38:39], 12, v[38:39]
	v_lshl_add_u64 v[38:39], v[16:17], 0, v[38:39]
	global_load_dword v35, v[18:19], off offset:20
	global_load_dword v26, v[38:39], off
	v_or_b32_e32 v38, 6, v14
	v_ashrrev_i32_e32 v39, 31, v38
	v_lshlrev_b64 v[38:39], 12, v[38:39]
	v_lshl_add_u64 v[38:39], v[16:17], 0, v[38:39]
	global_load_dword v36, v[18:19], off offset:24
	global_load_dword v29, v[38:39], off
	v_or_b32_e32 v38, 7, v14
	v_ashrrev_i32_e32 v39, 31, v38
	v_lshlrev_b64 v[38:39], 12, v[38:39]
	v_lshl_add_u64 v[38:39], v[16:17], 0, v[38:39]
	global_load_dword v37, v[18:19], off offset:28
	global_load_dword v28, v[38:39], off
	s_waitcnt vmcnt(0)
	v_mul_f32_e32 v4, v30, v4
	v_mul_f32_e32 v23, v31, v23
	v_mul_f32_e32 v25, v32, v25
	v_mul_f32_e32 v24, v33, v24
	v_mul_f32_e32 v27, v34, v27
	v_mul_f32_e32 v26, v35, v26
	v_mul_f32_e32 v29, v36, v29
	v_mul_f32_e32 v28, v37, v28
	s_branch .LBB0_101

; #define LAS __attribute__((address_space(3)))
; __device__ __forceinline__ bf16_t f2bf(float f) { return (bf16_t)(cvtpk(f, 0.f) & 0xffffu); }
; __device__ __forceinline__ float bf2f(bf16_t b) { return __uint_as_float(((unsigned)b) << 16); }
; __device__ __forceinline__ float fexp(float x) { return __builtin_amdgcn_exp2f(x * 1.4426950408889634f); }
; __device__ __forceinline__ float frcp(float x) { return __builtin_amdgcn_rcpf(x); }
; __device__ __forceinline__ int crow(int r, int hi) { return (r & 3) + 8 * (r >> 2) + 4 * hi; }
; __device__ __forceinline__ void gla_unit(LAS char* lds0, int b, int h, int dvh, bf16_t* Z, bf16_t* OT, const float* afw, const float* afb, const float* abw, const float* abb, bool dry) {
;     ...
;         float run = 0.f;
; #pragma unroll
;         for (int g = 0; g < 4; ++g) {
;             const float mine = cs[4 * g + 3]; const float oth = __shfl_xor(mine, 32);
;             const float off = run + (hi ? oth : 0.f);
; #pragma unroll
;             for (int j = 0; j < 4; ++j) cs[4 * g + j] += off;
;             run += mine + oth;
;         }
;         if (hi == 0) ((LAS float*)(lds + G_TOT))[I * 64 + 32 * J + r32] = run;
;         asm volatile("s_waitcnt lgkmcnt(0)\n\ts_barrier" ::: "memory");
;         const float t0v = ((LAS float*)(lds + G_TOT))[32 * J + r32], t1v = ((LAS float*)(lds + G_TOT))[64 + 32 * J + r32];
;         const float pre = I ? t0v : 0.f, tot = t0v + t1v;
;         const float etot = fexp(tot);
; #pragma unroll
;         for (int r = 0; r < 16; ++r) {
;             const int ii = 32 * I + crow(r, hi), dd = 32 * J + r32; const float eb = fexp(pre + cs[r]); const float ieb = frcp(eb);
;             LAS bf16_t* qp = (LAS bf16_t*)(lds + G_Q) + ii * (GP / 2) + dd; LAS bf16_t* kp = (LAS bf16_t*)(lds + G_K) + ii * (GP / 2) + dd;
;             const float qv = bf2f(*qp), kv = bf2f(*kp);
;             *qp = f2bf(qv * eb); *kp = f2bf(kv * ieb);
;             ((LAS bf16_t*)(lds + G_KD))[ii * (GP / 2) + dd] = f2bf(kv * ieb * etot);
;         }
.LBB0_414:
	s_or_b64 exec, exec, s[76:77]
	v_add_f32_e32 v51, 0, v51
	v_cndmask_b32_e64 v51, v51, 0, s[38:39]
	v_add_f32_e32 v57, v51, v34
	v_cndmask_b32_e64 v34, v53, 0, s[38:39]
	v_add_f32_e32 v34, v34, v50
	v_add_f32_e32 v58, v51, v44
	v_add_f32_e32 v59, v51, v45
	v_add_f32_e32 v49, v51, v49
	v_add_f32_e32 v50, v37, v34
	v_add_f32_e32 v51, v42, v34
	v_add_f32_e32 v45, v43, v34
	v_add_f32_e32 v44, v41, v34
	v_cndmask_b32_e64 v34, v55, 0, s[38:39]
	v_add_f32_e32 v34, v34, v52
	v_add_f32_e32 v43, v40, v34
	v_add_f32_e32 v42, v38, v34
	v_add_f32_e32 v41, v39, v34
	v_add_f32_e32 v40, v48, v34
	s_waitcnt lgkmcnt(0)
	v_cndmask_b32_e64 v34, v56, 0, s[38:39]
	v_add_f32_e32 v34, v34, v54
	s_waitcnt lgkmcnt(0)
	s_barrier
	v_add_f32_e32 v39, v46, v34
	v_add_f32_e32 v38, v35, v34
	ds_read_b32 v35, v132
	ds_read_b32 v46, v133 offset:256
	ds_read_u16 v206, v138
	ds_read_u16 v207, v138 offset:9216
	ds_read_u16 v208, v139
	ds_read_u16 v209, v139 offset:9216
	ds_read_u16 v210, v140
	ds_read_u16 v211, v140 offset:9216
	ds_read_u16 v212, v141
	ds_read_u16 v213, v141 offset:9216
	ds_read_u16 v214, v142
	ds_read_u16 v215, v142 offset:9216
	ds_read_u16 v216, v143
	ds_read_u16 v217, v143 offset:9216
	ds_read_u16 v218, v144
	ds_read_u16 v219, v144 offset:9216
	ds_read_u16 v220, v145
	ds_read_u16 v221, v145 offset:9216
	ds_read_u16 v222, v146
	ds_read_u16 v223, v146 offset:9216
	ds_read_u16 v224, v147
	ds_read_u16 v225, v147 offset:9216
	ds_read_u16 v226, v148
	ds_read_u16 v227, v148 offset:9216
	ds_read_u16 v228, v149
	ds_read_u16 v229, v149 offset:9216
	ds_read_u16 v230, v150
	ds_read_u16 v231, v150 offset:9216
	ds_read_u16 v232, v151
	ds_read_u16 v233, v151 offset:9216
	ds_read_u16 v234, v152
	ds_read_u16 v235, v152 offset:9216
	ds_read_u16 v236, v153
	ds_read_u16 v237, v153 offset:9216
	s_waitcnt lgkmcnt(0)
	v_add_f32_e32 v36, v36, v34
	v_cndmask_b32_e64 v37, v35, 0, s[34:35]
	v_add_f32_e32 v35, v35, v46
	v_add_f32_e32 v46, v57, v37
	v_mul_f32_e32 v46, 0x3fb8aa3b, v46
	v_exp_f32_e32 v46, v46
	v_add_f32_e32 v34, v47, v34
	v_mul_f32_e32 v35, 0x3fb8aa3b, v35
	v_exp_f32_e32 v35, v35
	v_rcp_f32_e32 v47, v46
	v_lshlrev_b32_e32 v48, 16, v206
	v_mul_f32_e32 v46, v46, v48
	v_lshlrev_b32_e32 v52, 16, v207
	v_cvt_pk_bf16_f32 v46, v46, s0
	ds_write_b16 v138, v46
	v_mul_f32_e32 v46, v47, v52
	v_cvt_pk_bf16_f32 v47, v46, s0
	v_mul_f32_e32 v46, v35, v46
	v_cvt_pk_bf16_f32 v46, v46, s0
	ds_write_b16 v138, v46 offset:18432
	v_add_f32_e32 v46, v58, v37
	v_mul_f32_e32 v46, 0x3fb8aa3b, v46
	v_exp_f32_e32 v46, v46
	ds_write_b16 v138, v47 offset:9216
	v_rcp_f32_e32 v47, v46
	v_add_f32_e32 v45, v45, v37
	v_lshlrev_b32_e32 v48, 16, v208
	v_mul_f32_e32 v46, v46, v48
	v_lshlrev_b32_e32 v52, 16, v209
	v_cvt_pk_bf16_f32 v46, v46, s0
	ds_write_b16 v139, v46
	v_mul_f32_e32 v46, v47, v52
	v_cvt_pk_bf16_f32 v47, v46, s0
	v_mul_f32_e32 v46, v35, v46
	v_cvt_pk_bf16_f32 v46, v46, s0
	ds_write_b16 v139, v46 offset:18432
	v_add_f32_e32 v46, v59, v37
	v_mul_f32_e32 v46, 0x3fb8aa3b, v46
	v_exp_f32_e32 v46, v46
	ds_write_b16 v139, v47 offset:9216
	v_rcp_f32_e32 v47, v46
	v_mul_f32_e32 v45, 0x3fb8aa3b, v45
	v_lshlrev_b32_e32 v48, 16, v210
	v_mul_f32_e32 v46, v46, v48
	v_lshlrev_b32_e32 v52, 16, v211
	v_cvt_pk_bf16_f32 v46, v46, s0
	ds_write_b16 v140, v46
	v_mul_f32_e32 v46, v47, v52
	v_cvt_pk_bf16_f32 v47, v46, s0
	v_mul_f32_e32 v46, v35, v46
	v_cvt_pk_bf16_f32 v46, v46, s0
	ds_write_b16 v140, v46 offset:18432
	v_add_f32_e32 v46, v49, v37
	v_mul_f32_e32 v46, 0x3fb8aa3b, v46
	v_exp_f32_e32 v46, v46
	ds_write_b16 v140, v47 offset:9216
	v_rcp_f32_e32 v47, v46
	v_exp_f32_e32 v45, v45
	v_lshlrev_b32_e32 v48, 16, v212
	v_mul_f32_e32 v46, v46, v48
	v_lshlrev_b32_e32 v49, 16, v213
	v_cvt_pk_bf16_f32 v46, v46, s0
	ds_write_b16 v141, v46
	v_mul_f32_e32 v46, v47, v49
	v_cvt_pk_bf16_f32 v47, v46, s0
	v_mul_f32_e32 v46, v35, v46
	v_cvt_pk_bf16_f32 v46, v46, s0
	ds_write_b16 v141, v46 offset:18432
	v_add_f32_e32 v46, v50, v37
	v_mul_f32_e32 v46, 0x3fb8aa3b, v46
	v_exp_f32_e32 v46, v46
	ds_write_b16 v141, v47 offset:9216
	v_rcp_f32_e32 v47, v46
	v_add_f32_e32 v44, v44, v37
	v_lshlrev_b32_e32 v48, 16, v214
	v_mul_f32_e32 v46, v46, v48
	v_lshlrev_b32_e32 v49, 16, v215
	v_cvt_pk_bf16_f32 v46, v46, s0
	ds_write_b16 v142, v46
	v_mul_f32_e32 v46, v47, v49
	v_cvt_pk_bf16_f32 v47, v46, s0
	v_mul_f32_e32 v46, v35, v46
	v_cvt_pk_bf16_f32 v46, v46, s0
	ds_write_b16 v142, v46 offset:18432
	v_add_f32_e32 v46, v51, v37
	v_mul_f32_e32 v46, 0x3fb8aa3b, v46
	v_exp_f32_e32 v46, v46
	ds_write_b16 v142, v47 offset:9216
	v_rcp_f32_e32 v47, v46
	v_mul_f32_e32 v44, 0x3fb8aa3b, v44
	v_lshlrev_b32_e32 v48, 16, v216
	v_mul_f32_e32 v46, v46, v48
	v_lshlrev_b32_e32 v49, 16, v217
	v_cvt_pk_bf16_f32 v46, v46, s0
	ds_write_b16 v143, v46
	v_mul_f32_e32 v46, v47, v49
	v_cvt_pk_bf16_f32 v47, v46, s0
	ds_write_b16 v143, v47 offset:9216
	v_mul_f32_e32 v46, v35, v46
	v_cvt_pk_bf16_f32 v46, v46, s0
	ds_write_b16 v143, v46 offset:18432
	v_rcp_f32_e32 v46, v45
	v_lshlrev_b32_e32 v47, 16, v218
	v_mul_f32_e32 v45, v45, v47
	v_lshlrev_b32_e32 v48, 16, v219
	v_cvt_pk_bf16_f32 v45, v45, s0
	ds_write_b16 v144, v45
	v_mul_f32_e32 v45, v46, v48
	v_cvt_pk_bf16_f32 v46, v45, s0
; #define LAS __attribute__((address_space(3)))
; __device__ __forceinline__ bf16_t f2bf(float f) { return (bf16_t)(cvtpk(f, 0.f) & 0xffffu); }
; __device__ __forceinline__ float bf2f(bf16_t b) { return __uint_as_float(((unsigned)b) << 16); }
; __device__ __forceinline__ float fexp(float x) { return __builtin_amdgcn_exp2f(x * 1.4426950408889634f); }
; __device__ __forceinline__ float frcp(float x) { return __builtin_amdgcn_rcpf(x); }
; __device__ __forceinline__ int crow(int r, int hi) { return (r & 3) + 8 * (r >> 2) + 4 * hi; }
; __device__ __forceinline__ void gla_unit(LAS char* lds0, int b, int h, int dvh, bf16_t* Z, bf16_t* OT, const float* afw, const float* afb, const float* abw, const float* abb, bool dry) {
;     ...
;         for (int r = 0; r < 16; ++r) {
;             const int ii = 32 * I + crow(r, hi), dd = 32 * J + r32; const float eb = fexp(pre + cs[r]); const float ieb = frcp(eb);
;             LAS bf16_t* qp = (LAS bf16_t*)(lds + G_Q) + ii * (GP / 2) + dd; LAS bf16_t* kp = (LAS bf16_t*)(lds + G_K) + ii * (GP / 2) + dd;
;             const float qv = bf2f(*qp), kv = bf2f(*kp);
;             *qp = f2bf(qv * eb); *kp = f2bf(kv * ieb);
;             ((LAS bf16_t*)(lds + G_KD))[ii * (GP / 2) + dd] = f2bf(kv * ieb * etot);
;         }
;         if (I == 0 && hi == 0) ((LAS float*)(lds + G_DEC))[32 * J + r32] = etot;
;         asm volatile("s_waitcnt lgkmcnt(0)\n\ts_barrier" ::: "memory");
;         f32x16 oacc = {};
;         {
;             f32x16 Ac = {};
;             if (J <= I) {
; #pragma unroll
;                 for (int k = 0; k < 4; ++k) {
;                     const bf16x8 a = *(const LAS bf16x8*)(lds + G_Q + (32 * I + r32) * GP + (16 * k + 8 * hi) * 2);
;                     const bf16x8 bq = *(const LAS bf16x8*)(lds + G_K + (32 * J + r32) * GP + (16 * k + 8 * hi) * 2);
;                     Ac = __builtin_amdgcn_mfma_f32_32x32x16_bf16(a, bq, Ac, 0, 0, 0);
;                 }
	v_mul_f32_e32 v45, v35, v45
	v_cvt_pk_bf16_f32 v45, v45, s0
	ds_write_b16 v144, v46 offset:9216
	ds_write_b16 v144, v45 offset:18432
	v_exp_f32_e32 v44, v44
	v_add_f32_e32 v43, v43, v37
	v_rcp_f32_e32 v45, v44
	v_mul_f32_e32 v43, 0x3fb8aa3b, v43
	v_lshlrev_b32_e32 v46, 16, v220
	v_mul_f32_e32 v44, v44, v46
	v_lshlrev_b32_e32 v47, 16, v221
	v_cvt_pk_bf16_f32 v44, v44, s0
	ds_write_b16 v145, v44
	v_mul_f32_e32 v44, v45, v47
	v_cvt_pk_bf16_f32 v45, v44, s0
	v_mul_f32_e32 v44, v35, v44
	v_cvt_pk_bf16_f32 v44, v44, s0
	ds_write_b16 v145, v45 offset:9216
	ds_write_b16 v145, v44 offset:18432
	v_exp_f32_e32 v43, v43
	v_add_f32_e32 v42, v42, v37
	v_rcp_f32_e32 v44, v43
	v_mul_f32_e32 v42, 0x3fb8aa3b, v42
	v_lshlrev_b32_e32 v45, 16, v222
	v_mul_f32_e32 v43, v43, v45
	v_lshlrev_b32_e32 v46, 16, v223
	v_cvt_pk_bf16_f32 v43, v43, s0
	ds_write_b16 v146, v43
	v_mul_f32_e32 v43, v44, v46
	v_cvt_pk_bf16_f32 v44, v43, s0
	v_mul_f32_e32 v43, v35, v43
	v_cvt_pk_bf16_f32 v43, v43, s0
	ds_write_b16 v146, v44 offset:9216
	ds_write_b16 v146, v43 offset:18432
	v_exp_f32_e32 v42, v42
	v_add_f32_e32 v41, v41, v37
	v_rcp_f32_e32 v43, v42
	v_mul_f32_e32 v41, 0x3fb8aa3b, v41
	v_lshlrev_b32_e32 v44, 16, v224
	v_mul_f32_e32 v42, v42, v44
	v_lshlrev_b32_e32 v45, 16, v225
	v_cvt_pk_bf16_f32 v42, v42, s0
	ds_write_b16 v147, v42
	v_mul_f32_e32 v42, v43, v45
	v_cvt_pk_bf16_f32 v43, v42, s0
	v_mul_f32_e32 v42, v35, v42
	v_cvt_pk_bf16_f32 v42, v42, s0
	ds_write_b16 v147, v43 offset:9216
	ds_write_b16 v147, v42 offset:18432
	v_exp_f32_e32 v41, v41
	v_add_f32_e32 v40, v40, v37
	v_rcp_f32_e32 v42, v41
	v_mul_f32_e32 v40, 0x3fb8aa3b, v40
	v_lshlrev_b32_e32 v43, 16, v226
	v_mul_f32_e32 v41, v41, v43
	v_lshlrev_b32_e32 v44, 16, v227
	v_cvt_pk_bf16_f32 v41, v41, s0
	ds_write_b16 v148, v41
	v_mul_f32_e32 v41, v42, v44
	v_cvt_pk_bf16_f32 v42, v41, s0
	v_mul_f32_e32 v41, v35, v41
	v_cvt_pk_bf16_f32 v41, v41, s0
	ds_write_b16 v148, v42 offset:9216
	ds_write_b16 v148, v41 offset:18432
	v_exp_f32_e32 v40, v40
	v_add_f32_e32 v39, v39, v37
	v_rcp_f32_e32 v41, v40
	v_mul_f32_e32 v39, 0x3fb8aa3b, v39
	v_lshlrev_b32_e32 v42, 16, v228
	v_mul_f32_e32 v40, v40, v42
	v_lshlrev_b32_e32 v43, 16, v229
	v_cvt_pk_bf16_f32 v40, v40, s0
	ds_write_b16 v149, v40
	v_mul_f32_e32 v40, v41, v43
	v_cvt_pk_bf16_f32 v41, v40, s0
	v_mul_f32_e32 v40, v35, v40
	v_cvt_pk_bf16_f32 v40, v40, s0
	ds_write_b16 v149, v41 offset:9216
	ds_write_b16 v149, v40 offset:18432
	v_exp_f32_e32 v39, v39
	v_add_f32_e32 v38, v38, v37
	v_rcp_f32_e32 v40, v39
	v_mul_f32_e32 v38, 0x3fb8aa3b, v38
	v_lshlrev_b32_e32 v41, 16, v230
	v_mul_f32_e32 v39, v39, v41
	v_lshlrev_b32_e32 v42, 16, v231
	v_cvt_pk_bf16_f32 v39, v39, s0
	ds_write_b16 v150, v39
	v_mul_f32_e32 v39, v40, v42
	v_cvt_pk_bf16_f32 v40, v39, s0
	v_mul_f32_e32 v39, v35, v39
	v_cvt_pk_bf16_f32 v39, v39, s0
	ds_write_b16 v150, v40 offset:9216
	ds_write_b16 v150, v39 offset:18432
	v_exp_f32_e32 v38, v38
	v_add_f32_e32 v36, v36, v37
	v_rcp_f32_e32 v39, v38
	v_mul_f32_e32 v36, 0x3fb8aa3b, v36
	v_lshlrev_b32_e32 v40, 16, v232
	v_mul_f32_e32 v38, v38, v40
	v_lshlrev_b32_e32 v41, 16, v233
	v_cvt_pk_bf16_f32 v38, v38, s0
	ds_write_b16 v151, v38
	v_mul_f32_e32 v38, v39, v41
	v_cvt_pk_bf16_f32 v39, v38, s0
	v_mul_f32_e32 v38, v35, v38
	v_cvt_pk_bf16_f32 v38, v38, s0
	ds_write_b16 v151, v39 offset:9216
	ds_write_b16 v151, v38 offset:18432
	v_exp_f32_e32 v36, v36
	v_add_f32_e32 v34, v34, v37
	v_rcp_f32_e32 v38, v36
	v_mul_f32_e32 v34, 0x3fb8aa3b, v34
	v_lshlrev_b32_e32 v39, 16, v234
	v_mul_f32_e32 v36, v36, v39
	v_lshlrev_b32_e32 v40, 16, v235
	v_cvt_pk_bf16_f32 v36, v36, s0
	ds_write_b16 v152, v36
	v_mul_f32_e32 v36, v38, v40
	v_cvt_pk_bf16_f32 v38, v36, s0
	v_mul_f32_e32 v36, v35, v36
	v_cvt_pk_bf16_f32 v36, v36, s0
	ds_write_b16 v152, v38 offset:9216
	ds_write_b16 v152, v36 offset:18432
	v_exp_f32_e32 v34, v34
	v_rcp_f32_e32 v36, v34
	v_lshlrev_b32_e32 v37, 16, v236
	v_mul_f32_e32 v34, v34, v37
	v_lshlrev_b32_e32 v38, 16, v237
	v_cvt_pk_bf16_f32 v34, v34, s0
	ds_write_b16 v153, v34
	v_mul_f32_e32 v34, v36, v38
	v_cvt_pk_bf16_f32 v36, v34, s0
	v_mul_f32_e32 v34, v35, v34
	v_cvt_pk_bf16_f32 v34, v34, s0
	ds_write_b16 v153, v36 offset:9216
	ds_write_b16 v153, v34 offset:18432
	s_and_saveexec_b64 s[76:77], s[40:41]
	ds_write_b32 v134, v35
	s_or_b64 exec, exec, s[76:77]
	s_waitcnt lgkmcnt(0)
	s_barrier
	v_add_u32_e32 v172, v135, v117
	ds_read_b128 v[50:53], v172
	s_mov_b64 s[76:77], -1
	s_and_b64 vcc, exec, s[78:79]
	s_cbranch_vccz .LBB0_418
	v_add_u32_e32 v58, v136, v117
	ds_read_b128 v[34:37], v58 offset:9216
	ds_read_b128 v[54:57], v58 offset:9248
	ds_read_b128 v[106:109], v172 offset:32
	ds_read_b128 v[102:105], v172 offset:64
	s_mov_b64 s[76:77], 0
	s_waitcnt lgkmcnt(3)
	v_mfma_f32_32x32x16_bf16 v[34:49], v[50:53], v[34:37], 0
	s_waitcnt lgkmcnt(1)
	v_mfma_f32_32x32x16_bf16 v[34:49], v[106:109], v[54:57], v[34:49]
	ds_read_b128 v[54:57], v58 offset:9280
	s_waitcnt lgkmcnt(0)
	v_mfma_f32_32x32x16_bf16 v[34:49], v[102:105], v[54:57], v[34:49]
	ds_read_b128 v[110:113], v172 offset:96
	ds_read_b128 v[54:57], v58 offset:9312
	s_waitcnt lgkmcnt(0)
	v_mfma_f32_32x32x16_bf16 v[34:49], v[110:113], v[54:57], v[34:49]
